# peeled first K iteration (srcC=0, no zeroing) + first-iteration waits relaxed so previous tile's epilogue stores stay in flight (vmcnt 8+NS at ph4, vmcnt(10) at ph6), prologue vmcnt(0)
# speedup vs baseline: 1.0067x; 1.0067x over previous
; #define PG8_STAGE(bufoff, gbase, voff) do { _Pragma("unroll") for (int _i = 0; _i < 2; ++_i) \
;         __builtin_amdgcn_global_load_lds((const unsigned*)((const char*)(gbase) + (voff)[_i]), (LAS unsigned*)(lds + (bufoff) + ldsw + _i * 8192), 16, 0, 0); } while (0)
; #define PG8_WAIT_V(n) asm volatile("s_waitcnt vmcnt(" #n ")" ::: "memory")
; #define PG8_BAR __builtin_amdgcn_s_barrier()
; #define tid fresh_tid(wave_s)
; template <class Epi, class Sched>
; __device__ __forceinline__ void gemm_phase(LAS unsigned char* lds, const Gemm g, const Sched& S, const Epi& E, int tid) {
;     ...
;     for (int i = 0; i < 2; ++i) { int R, C; stage_rc(tid * 16 + i * 8192, R, C); const int Rb = Epi::PERM ? ((R & ~31) + perm32(R & 31)) : R;
;         voffA[i] = (unsigned)(R * K + C) * 2u; voffB[i] = (unsigned)(Rb * K + C) * 2u; }
;     const size_t kstep = (size_t)(BK * 2);
;     const size_t hstep = (size_t)HALF * K * 2;
;     const size_t tstep = 2 * hstep;
;     const unsigned ldsw = (unsigned)wid * 1024u;
;     const int aoff = lds_byte(wr * 64 + fr, fq * 8), boff = lds_byte(wc * 32 + fr, fq * 8);
;     ...
;     Unit cur, nxt; int ui = 0;
;     if (!S.next(0, cur)) return;
;     f32x4 acc[2][2][4][2];
; #pragma unroll
;     for (int a = 0; a < 2; ++a)
; #pragma unroll
;         for (int b = 0; b < 2; ++b)
; #pragma unroll
;             for (int m = 0; m < 4; ++m)
; #pragma unroll
;                 for (int n = 0; n < 2; ++n) acc[a][b][m][n] = (f32x4){0.f, 0.f, 0.f, 0.f};
;     bf16x8 At[4][2], B0[2][2], B1[2][2];
;     const char* cA = (const char*)g.A + (size_t)cur.pm * tstep; const char* cB = (const char*)g.Bt + (size_t)cur.pn * tstep;
;     PG8_STAGE(PG8_SB(0, 0), cB, voffB); PG8_STAGE(PG8_SA(0, 0), cA, voffA); PG8_STAGE(PG8_SB(0, 1), cB + hstep, voffB); PG8_STAGE(PG8_SA(0, 1), cA + hstep, voffA);
;     if (wr == 1) PG8_BAR;
;     PG8_WAIT_V(4); PG8_BAR;
;     PG8_STAGE(PG8_SB(1, 0), cB + kstep, voffB); PG8_STAGE(PG8_SA(1, 0), cA + kstep, voffA); PG8_STAGE(PG8_SB(1, 1), cB + hstep + kstep, voffB);
;     PG8_WAIT_V(6); PG8_BAR;
.LBB0_88:
	s_add_i32 m0, s88, 0x18000
	v_lshl_add_u64 v[10:11], v[10:11], 0, s[8:9]
	s_waitcnt vmcnt(4)
	s_barrier
	global_load_lds_dwordx4 v[10:11], off
	v_lshl_add_u64 v[8:9], v[8:9], 0, s[8:9]
	s_add_i32 m0, s88, 0x1a000
	s_add_i32 s92, s88, 0x8000
	global_load_lds_dwordx4 v[8:9], off
	v_lshl_add_u64 v[6:7], v[6:7], 0, s[8:9]
	s_mov_b32 m0, s92
	s_add_i32 s93, s88, 0xa000
	global_load_lds_dwordx4 v[6:7], off
	v_lshl_add_u64 v[4:5], v[4:5], 0, s[8:9]
	s_mov_b32 m0, s93
	v_lshl_add_u64 v[2:3], v[2:3], 0, s[8:9]
	global_load_lds_dwordx4 v[4:5], off
	s_add_i32 m0, s88, 0x1c000
	v_lshl_add_u64 v[0:1], v[0:1], 0, s[8:9]
	global_load_lds_dwordx4 v[2:3], off
	s_add_i32 m0, s88, 0x1e000
	s_lshr_b32 s94, s0, 6
	global_load_lds_dwordx4 v[0:1], off
	v_lshrrev_b32_e32 v1, 1, v12
	v_and_b32_e32 v1, 24, v1
	v_and_b32_e32 v0, 15, v12
	v_lshlrev_b32_e32 v2, 1, v1
	v_lshl_or_b32 v140, s37, 6, v0
	v_lshl_or_b32 v0, v0, 6, v2
	v_lshlrev_b32_e32 v2, 2, v12
	s_lshl_b32 s0, s37, 13
	v_and_b32_e32 v2, 32, v2
	v_bitop3_b32 v3, v0, s0, v2 bitop3:0xde
	s_lshl_b32 s0, s1, 5
	s_and_b32 s0, s0, 0x60
	s_lshl_b32 s1, s0, 7
	v_bitop3_b32 v141, s1, v0, v2 bitop3:0xf6
	v_add_u32_e32 v0, v15, v13
	v_or_b32_e32 v142, s0, v1
	v_add_lshl_u32 v0, v0, v14, 1
	v_mov_b32_e32 v1, v155
	s_waitcnt vmcnt(0)
	v_lshl_add_u64 v[134:135], s[6:7], 0, v[0:1]
	v_add_u32_e32 v0, v18, v16
	s_mov_b32 s37, s7
	v_add_lshl_u32 v0, v0, v17, 1
	s_sext_i32_i16 s61, s38
	s_add_i32 s95, s94, -2
	v_lshl_add_u64 v[136:137], s[6:7], 0, v[0:1]
	s_mov_b32 s55, 0
	v_add_u32_e32 v143, 0, v3
	v_mov_b64_e32 v[138:139], s[36:37]
	s_barrier

; #define PG8_STAGE(bufoff, gbase, voff) do { _Pragma("unroll") for (int _i = 0; _i < 2; ++_i) \
;         __builtin_amdgcn_global_load_lds((const unsigned*)((const char*)(gbase) + (voff)[_i]), (LAS unsigned*)(lds + (bufoff) + ldsw + _i * 8192), 16, 0, 0); } while (0)
; #define PG8_LDA(dst, b, h) do { _Pragma("unroll") for (int m = 0; m < 4; ++m) _Pragma("unroll") for (int k = 0; k < 2; ++k) dst[m][k] = *(const LAS bf16x8*)(lds + PG8_SA(b, h) + aoff + m * 2048 + k * 1024); } while (0)
; #define PG8_LDB(dst, b, h) do { _Pragma("unroll") for (int n = 0; n < 2; ++n) _Pragma("unroll") for (int k = 0; k < 2; ++k) dst[n][k] = *(const LAS bf16x8*)(lds + PG8_SB(b, h) + boff + n * 2048 + k * 1024); } while (0)
; #define PG8_MMA(ai, bj, At, Bt) do { __builtin_amdgcn_s_setprio(1); _Pragma("unroll") for (int m = 0; m < 4; ++m) _Pragma("unroll") for (int n = 0; n < 2; ++n) _Pragma("unroll") for (int k = 0; k < 2; ++k) \
;         acc[ai][bj][m][n] = __builtin_amdgcn_mfma_f32_16x16x32_bf16(Bt[n][k], At[m][k], acc[ai][bj][m][n], 0, 0, 0); __builtin_amdgcn_s_setprio(0); } while (0)
; #define PG8_WAIT_L(n) asm volatile("s_waitcnt lgkmcnt(" #n ")" ::: "memory")
; template <class Epi, class Sched>
; __device__ __forceinline__ void gemm_phase(LAS unsigned char* lds, const Gemm g, const Sched& S, const Epi& E, int tid) {
;     ...
;         const bool has_next = S.next(ui + 1, nxt);
;         const char* nA = has_next ? (const char*)g.A + (size_t)nxt.pm * tstep : cA; const char* nB = has_next ? (const char*)g.Bt + (size_t)nxt.pn * tstep : cB;
;         for (int t = 0; t < nt; t += 2) {
;             const bool last = (t == nt - 2);
;             const char* a1 = cA + (size_t)(t + 1) * kstep;
;             const char* a2 = last ? nA : cA + (size_t)(t + 2) * kstep; const char* b2 = last ? nB : cB + (size_t)(t + 2) * kstep;
;             const char* a3 = a2 + kstep; const char* b3 = b2 + kstep;
;             PG8_LDB(B0, 0, 0); PG8_SCHED; PG8_LDA(At, 0, 0); PG8_STAGE(PG8_SA(1, 1), a1 + hstep, voffA);
;             PG8_WAIT_L(8); PG8_BAR; PG8_WAIT_L(0); PG8_MMA(0, 0, At, B0); PG8_BAR; PG8_SCHED;
;             PG8_LDB(B1, 0, 1); PG8_STAGE(PG8_SB(0, 0), b2, voffB);
;             PG8_BAR; PG8_WAIT_L(0); PG8_MMA(0, 1, At, B1); PG8_BAR;
;             PG8_LDA(At, 0, 1); PG8_STAGE(PG8_SA(0, 0), a2, voffA);
;             PG8_BAR; PG8_WAIT_L(0); PG8_MMA(1, 0, At, B0); PG8_BAR; PG8_SCHED;
.LBB0_99:
	s_add_u32 vcc_lo, s44, 0x80
	s_addc_u32 vcc_hi, s45, 0
	s_add_u32 s96, s34, 0x100
	s_addc_u32 s65, s35, 0
	s_mov_b32 s34, 0
	s_add_i32 s0, s34, 2
	s_add_u32 s1, vcc_lo, 0x80
	s_addc_u32 s35, vcc_hi, 0
	s_add_i32 s17, 0, 0x10000
	v_add_u32_e32 v152, s17, v141
	ds_read_b128 v[144:147], v152
	ds_read_b128 v[148:151], v152 offset:1024
	ds_read_b128 v[160:163], v152 offset:2048
	ds_read_b128 v[164:167], v152 offset:3072
	s_cmp_eq_u32 s95, s34
	s_cselect_b32 s34, s38, s1
	s_cselect_b32 s35, s39, s35
	s_cselect_b32 s45, s41, s65
	s_cselect_b32 s44, s40, s96
	v_lshl_add_u64 v[152:153], vcc, 0, v[134:135]
	s_add_i32 m0, s88, 0xc000
	ds_read_b128 v[168:171], v143
	ds_read_b128 v[184:187], v143 offset:1024
	ds_read_b128 v[188:191], v143 offset:2048
	ds_read_b128 v[192:195], v143 offset:3072
	ds_read_b128 v[196:199], v143 offset:4096
	ds_read_b128 v[200:203], v143 offset:5120
	ds_read_b128 v[204:207], v143 offset:6144
	ds_read_b128 v[208:211], v143 offset:7168
	global_load_lds_dwordx4 v[152:153], off
	v_lshl_add_u64 v[152:153], vcc, 0, v[136:137]
	s_add_i32 m0, s88, 0xe000
	s_nop 0
	global_load_lds_dwordx4 v[152:153], off
	s_waitcnt lgkmcnt(8)
	s_barrier
	s_waitcnt lgkmcnt(0)
	s_setprio 1
	s_waitcnt lgkmcnt(0)
	v_mfma_f32_16x16x32_bf16 v[124:127], v[144:147], v[168:171], 0
	v_mfma_f32_16x16x32_bf16 v[120:123], v[160:163], v[168:171], 0
	v_mfma_f32_16x16x32_bf16 v[116:119], v[144:147], v[188:191], 0
	v_mfma_f32_16x16x32_bf16 v[112:115], v[160:163], v[188:191], 0
	v_mfma_f32_16x16x32_bf16 v[100:103], v[144:147], v[196:199], 0
	v_mfma_f32_16x16x32_bf16 v[96:99], v[160:163], v[196:199], 0
	v_mfma_f32_16x16x32_bf16 v[84:87], v[144:147], v[204:207], 0
	v_mfma_f32_16x16x32_bf16 v[80:83], v[160:163], v[204:207], 0
	v_mfma_f32_16x16x32_bf16 v[124:127], v[148:151], v[184:187], v[124:127]
	v_mfma_f32_16x16x32_bf16 v[120:123], v[164:167], v[184:187], v[120:123]
	v_mfma_f32_16x16x32_bf16 v[116:119], v[148:151], v[192:195], v[116:119]
	v_mfma_f32_16x16x32_bf16 v[112:115], v[164:167], v[192:195], v[112:115]
	v_mfma_f32_16x16x32_bf16 v[100:103], v[148:151], v[200:203], v[100:103]
	v_mfma_f32_16x16x32_bf16 v[96:99], v[164:167], v[200:203], v[96:99]
	v_mfma_f32_16x16x32_bf16 v[84:87], v[148:151], v[208:211], v[84:87]
	v_mfma_f32_16x16x32_bf16 v[80:83], v[164:167], v[208:211], v[80:83]
	s_setprio 0
	s_barrier
	s_add_i32 s1, 0, 0x14000
	v_add_u32_e32 v152, s1, v141
	s_add_i32 s17, s17, s85
	ds_read_b128 v[212:215], v152
	ds_read_b128 v[216:219], v152 offset:1024
	ds_read_b128 v[220:223], v152 offset:2048
	ds_read_b128 v[224:227], v152 offset:3072
	v_lshl_add_u64 v[152:153], s[44:45], 0, v[154:155]
	s_mov_b32 m0, s17
	v_lshl_add_u64 v[228:229], s[44:45], 0, v[132:133]
	global_load_lds_dwordx4 v[152:153], off
	s_add_i32 m0, s17, 0x2000
	s_nop 0
	global_load_lds_dwordx4 v[228:229], off
	s_barrier
	s_waitcnt lgkmcnt(0)
	s_setprio 1
	s_waitcnt lgkmcnt(0)
	v_mfma_f32_16x16x32_bf16 v[108:111], v[212:215], v[168:171], 0
	v_mfma_f32_16x16x32_bf16 v[104:107], v[220:223], v[168:171], 0
	v_mfma_f32_16x16x32_bf16 v[92:95], v[212:215], v[188:191], 0
	v_mfma_f32_16x16x32_bf16 v[88:91], v[220:223], v[188:191], 0
	v_mfma_f32_16x16x32_bf16 v[76:79], v[212:215], v[196:199], 0
	v_mfma_f32_16x16x32_bf16 v[72:75], v[220:223], v[196:199], 0
	v_mfma_f32_16x16x32_bf16 v[68:71], v[212:215], v[204:207], 0
	v_mfma_f32_16x16x32_bf16 v[64:67], v[220:223], v[204:207], 0
	v_mfma_f32_16x16x32_bf16 v[108:111], v[216:219], v[184:187], v[108:111]
	v_mfma_f32_16x16x32_bf16 v[104:107], v[224:227], v[184:187], v[104:107]
	v_mfma_f32_16x16x32_bf16 v[92:95], v[216:219], v[192:195], v[92:95]
	v_mfma_f32_16x16x32_bf16 v[88:91], v[224:227], v[192:195], v[88:91]
	v_mfma_f32_16x16x32_bf16 v[76:79], v[216:219], v[200:203], v[76:79]
	v_mfma_f32_16x16x32_bf16 v[72:75], v[224:227], v[200:203], v[72:75]
	v_mfma_f32_16x16x32_bf16 v[68:71], v[216:219], v[208:211], v[68:71]
	v_mfma_f32_16x16x32_bf16 v[64:67], v[224:227], v[208:211], v[64:67]
	s_setprio 0
	s_mov_b32 m0, s88
	v_lshl_add_u64 v[230:231], s[34:35], 0, v[128:129]
	s_barrier
	ds_read_b128 v[168:171], v143 offset:16384
	ds_read_b128 v[184:187], v143 offset:17408
	ds_read_b128 v[188:191], v143 offset:18432
	ds_read_b128 v[192:195], v143 offset:19456
	ds_read_b128 v[196:199], v143 offset:20480
	ds_read_b128 v[200:203], v143 offset:21504
	ds_read_b128 v[204:207], v143 offset:22528
	ds_read_b128 v[208:211], v143 offset:23552
	global_load_lds_dwordx4 v[230:231], off
	v_lshl_add_u64 v[232:233], s[34:35], 0, v[130:131]
	s_mov_b32 m0, s89
	s_nop 0
	global_load_lds_dwordx4 v[232:233], off
	s_barrier
	s_waitcnt lgkmcnt(0)
	s_setprio 1
	s_waitcnt lgkmcnt(0)
	v_mfma_f32_16x16x32_bf16 v[60:63], v[144:147], v[168:171], 0
	v_mfma_f32_16x16x32_bf16 v[56:59], v[160:163], v[168:171], 0
	v_mfma_f32_16x16x32_bf16 v[52:55], v[144:147], v[188:191], 0
	v_mfma_f32_16x16x32_bf16 v[48:51], v[160:163], v[188:191], 0
	v_mfma_f32_16x16x32_bf16 v[36:39], v[144:147], v[196:199], 0
	v_mfma_f32_16x16x32_bf16 v[32:35], v[160:163], v[196:199], 0
	v_mfma_f32_16x16x32_bf16 v[20:23], v[144:147], v[204:207], 0
	v_mfma_f32_16x16x32_bf16 v[16:19], v[160:163], v[204:207], 0
	v_mfma_f32_16x16x32_bf16 v[60:63], v[148:151], v[184:187], v[60:63]
	v_mfma_f32_16x16x32_bf16 v[56:59], v[164:167], v[184:187], v[56:59]
	v_mfma_f32_16x16x32_bf16 v[52:55], v[148:151], v[192:195], v[52:55]
	v_mfma_f32_16x16x32_bf16 v[48:51], v[164:167], v[192:195], v[48:51]
	v_mfma_f32_16x16x32_bf16 v[36:39], v[148:151], v[200:203], v[36:39]
	v_mfma_f32_16x16x32_bf16 v[32:35], v[164:167], v[200:203], v[32:35]
	v_mfma_f32_16x16x32_bf16 v[20:23], v[148:151], v[208:211], v[20:23]
	v_mfma_f32_16x16x32_bf16 v[16:19], v[164:167], v[208:211], v[16:19]
	s_setprio 0
	s_barrier
; #define PG8_STAGE(bufoff, gbase, voff) do { _Pragma("unroll") for (int _i = 0; _i < 2; ++_i) \
;         __builtin_amdgcn_global_load_lds((const unsigned*)((const char*)(gbase) + (voff)[_i]), (LAS unsigned*)(lds + (bufoff) + ldsw + _i * 8192), 16, 0, 0); } while (0)
; #define PG8_LDA(dst, b, h) do { _Pragma("unroll") for (int m = 0; m < 4; ++m) _Pragma("unroll") for (int k = 0; k < 2; ++k) dst[m][k] = *(const LAS bf16x8*)(lds + PG8_SA(b, h) + aoff + m * 2048 + k * 1024); } while (0)
; #define PG8_LDB(dst, b, h) do { _Pragma("unroll") for (int n = 0; n < 2; ++n) _Pragma("unroll") for (int k = 0; k < 2; ++k) dst[n][k] = *(const LAS bf16x8*)(lds + PG8_SB(b, h) + boff + n * 2048 + k * 1024); } while (0)
; #define PG8_MMA(ai, bj, At, Bt) do { __builtin_amdgcn_s_setprio(1); _Pragma("unroll") for (int m = 0; m < 4; ++m) _Pragma("unroll") for (int n = 0; n < 2; ++n) _Pragma("unroll") for (int k = 0; k < 2; ++k) \
;         acc[ai][bj][m][n] = __builtin_amdgcn_mfma_f32_16x16x32_bf16(Bt[n][k], At[m][k], acc[ai][bj][m][n], 0, 0, 0); __builtin_amdgcn_s_setprio(0); } while (0)
; #define PG8_WAIT_V(n) asm volatile("s_waitcnt vmcnt(" #n ")" ::: "memory")
; #define PG8_WAIT_L(n) asm volatile("s_waitcnt lgkmcnt(" #n ")" ::: "memory")
; #define PG8_BAR __builtin_amdgcn_s_barrier()
; #define PG8_SCHED __builtin_amdgcn_sched_barrier(0)
; template <class Epi, class Sched>
; __device__ __forceinline__ void gemm_phase(LAS unsigned char* lds, const Gemm g, const Sched& S, const Epi& E, int tid) {
;     ...
;             PG8_STAGE(PG8_SB(0, 1), b2 + hstep, voffB);
;             PG8_WAIT_V(6); PG8_BAR; PG8_MMA(1, 1, At, B1); PG8_BAR;
;             PG8_LDB(B0, 1, 0); PG8_SCHED; PG8_LDA(At, 1, 0); PG8_STAGE(PG8_SA(0, 1), a2 + hstep, voffA);
;             PG8_WAIT_L(8); PG8_BAR; PG8_WAIT_L(0); PG8_MMA(0, 0, At, B0); PG8_BAR; PG8_SCHED;
;             PG8_LDB(B1, 1, 1); PG8_STAGE(PG8_SB(1, 0), b3, voffB);
;             PG8_BAR; PG8_WAIT_L(0); PG8_MMA(0, 1, At, B1); PG8_BAR;
	s_add_u32 s44, s44, s6
	s_addc_u32 s45, s45, 0
	s_add_i32 s1, s1, s85
	v_lshl_add_u64 v[234:235], s[44:45], 0, v[154:155]
	s_mov_b32 m0, s1
	v_lshl_add_u64 v[236:237], s[44:45], 0, v[132:133]
	global_load_lds_dwordx4 v[234:235], off
	s_add_i32 m0, s1, 0x2000
	s_nop 0
	global_load_lds_dwordx4 v[236:237], off
	s_waitcnt vmcnt(24)
	s_barrier
	s_setprio 1
	v_mfma_f32_16x16x32_bf16 v[44:47], v[212:215], v[168:171], 0
	v_mfma_f32_16x16x32_bf16 v[40:43], v[220:223], v[168:171], 0
	v_mfma_f32_16x16x32_bf16 v[28:31], v[212:215], v[188:191], 0
	v_mfma_f32_16x16x32_bf16 v[24:27], v[220:223], v[188:191], 0
	v_mfma_f32_16x16x32_bf16 v[12:15], v[212:215], v[196:199], 0
	v_mfma_f32_16x16x32_bf16 v[8:11], v[220:223], v[196:199], 0
	v_mfma_f32_16x16x32_bf16 v[4:7], v[212:215], v[204:207], 0
	v_mfma_f32_16x16x32_bf16 v[0:3], v[220:223], v[204:207], 0
	v_mfma_f32_16x16x32_bf16 v[44:47], v[216:219], v[184:187], v[44:47]
	v_mfma_f32_16x16x32_bf16 v[40:43], v[224:227], v[184:187], v[40:43]
	v_mfma_f32_16x16x32_bf16 v[28:31], v[216:219], v[192:195], v[28:31]
	v_mfma_f32_16x16x32_bf16 v[24:27], v[224:227], v[192:195], v[24:27]
	v_mfma_f32_16x16x32_bf16 v[12:15], v[216:219], v[200:203], v[12:15]
	v_mfma_f32_16x16x32_bf16 v[8:11], v[224:227], v[200:203], v[8:11]
	v_mfma_f32_16x16x32_bf16 v[4:7], v[216:219], v[208:211], v[4:7]
	v_mfma_f32_16x16x32_bf16 v[0:3], v[224:227], v[208:211], v[0:3]
	s_setprio 0
	s_add_i32 s1, 0, 0x18000
	v_add_u32_e32 v164, s1, v141
	s_barrier
	ds_read_b128 v[144:147], v164
	ds_read_b128 v[148:151], v164 offset:1024
	ds_read_b128 v[160:163], v164 offset:2048
	ds_read_b128 v[164:167], v164 offset:3072
	s_add_u32 s34, s34, s6
	s_addc_u32 s35, s35, 0
	s_mov_b32 m0, s90
	v_lshl_add_u64 v[212:213], s[34:35], 0, v[128:129]
	ds_read_b128 v[168:171], v143 offset:32768
	ds_read_b128 v[184:187], v143 offset:33792
	ds_read_b128 v[188:191], v143 offset:34816
	ds_read_b128 v[192:195], v143 offset:35840
	ds_read_b128 v[196:199], v143 offset:36864
	ds_read_b128 v[200:203], v143 offset:37888
	ds_read_b128 v[204:207], v143 offset:38912
	ds_read_b128 v[208:211], v143 offset:39936
	global_load_lds_dwordx4 v[212:213], off
	v_lshl_add_u64 v[212:213], s[34:35], 0, v[130:131]
	s_mov_b32 m0, s91
	s_nop 0
	global_load_lds_dwordx4 v[212:213], off
	s_waitcnt lgkmcnt(8)
	s_barrier
	s_waitcnt lgkmcnt(0)
	s_setprio 1
	s_waitcnt lgkmcnt(0)
	v_mfma_f32_16x16x32_bf16 v[124:127], v[144:147], v[168:171], v[124:127]
	v_mfma_f32_16x16x32_bf16 v[120:123], v[160:163], v[168:171], v[120:123]
	v_mfma_f32_16x16x32_bf16 v[116:119], v[144:147], v[188:191], v[116:119]
	v_mfma_f32_16x16x32_bf16 v[112:115], v[160:163], v[188:191], v[112:115]
	v_mfma_f32_16x16x32_bf16 v[100:103], v[144:147], v[196:199], v[100:103]
	v_mfma_f32_16x16x32_bf16 v[96:99], v[160:163], v[196:199], v[96:99]
	v_mfma_f32_16x16x32_bf16 v[84:87], v[144:147], v[204:207], v[84:87]
	v_mfma_f32_16x16x32_bf16 v[80:83], v[160:163], v[204:207], v[80:83]
	v_mfma_f32_16x16x32_bf16 v[124:127], v[148:151], v[184:187], v[124:127]
	v_mfma_f32_16x16x32_bf16 v[120:123], v[164:167], v[184:187], v[120:123]
	v_mfma_f32_16x16x32_bf16 v[116:119], v[148:151], v[192:195], v[116:119]
	v_mfma_f32_16x16x32_bf16 v[112:115], v[164:167], v[192:195], v[112:115]
	v_mfma_f32_16x16x32_bf16 v[100:103], v[148:151], v[200:203], v[100:103]
	v_mfma_f32_16x16x32_bf16 v[96:99], v[164:167], v[200:203], v[96:99]
	v_mfma_f32_16x16x32_bf16 v[84:87], v[148:151], v[208:211], v[84:87]
	v_mfma_f32_16x16x32_bf16 v[80:83], v[164:167], v[208:211], v[80:83]
	s_setprio 0
	s_barrier
	s_add_i32 s17, 0, 0x1c000
	s_add_i32 s1, s1, s85
	v_add_u32_e32 v183, s17, v141
	v_lshl_add_u64 v[152:153], v[152:153], 0, s[8:9]
	s_mov_b32 m0, s1
	ds_read_b128 v[212:215], v183
	ds_read_b128 v[216:219], v183 offset:1024
	ds_read_b128 v[220:223], v183 offset:2048
	ds_read_b128 v[224:227], v183 offset:3072
	global_load_lds_dwordx4 v[152:153], off
	v_lshl_add_u64 v[152:153], v[228:229], 0, s[8:9]
	s_add_i32 m0, s1, 0x2000
	s_nop 0
	global_load_lds_dwordx4 v[152:153], off
	s_waitcnt vmcnt(10)
	s_barrier
; #define PG8_STAGE(bufoff, gbase, voff) do { _Pragma("unroll") for (int _i = 0; _i < 2; ++_i) \
;         __builtin_amdgcn_global_load_lds((const unsigned*)((const char*)(gbase) + (voff)[_i]), (LAS unsigned*)(lds + (bufoff) + ldsw + _i * 8192), 16, 0, 0); } while (0)
; #define PG8_LDA(dst, b, h) do { _Pragma("unroll") for (int m = 0; m < 4; ++m) _Pragma("unroll") for (int k = 0; k < 2; ++k) dst[m][k] = *(const LAS bf16x8*)(lds + PG8_SA(b, h) + aoff + m * 2048 + k * 1024); } while (0)
; #define PG8_MMA(ai, bj, At, Bt) do { __builtin_amdgcn_s_setprio(1); _Pragma("unroll") for (int m = 0; m < 4; ++m) _Pragma("unroll") for (int n = 0; n < 2; ++n) _Pragma("unroll") for (int k = 0; k < 2; ++k) \
;         acc[ai][bj][m][n] = __builtin_amdgcn_mfma_f32_16x16x32_bf16(Bt[n][k], At[m][k], acc[ai][bj][m][n], 0, 0, 0); __builtin_amdgcn_s_setprio(0); } while (0)
; #define PG8_WAIT_V(n) asm volatile("s_waitcnt vmcnt(" #n ")" ::: "memory")
; #define PG8_WAIT_L(n) asm volatile("s_waitcnt lgkmcnt(" #n ")" ::: "memory")
; #define PG8_BAR __builtin_amdgcn_s_barrier()
; #define PG8_SCHED __builtin_amdgcn_sched_barrier(0)
; template <class Epi, class Sched>
; __device__ __forceinline__ void gemm_phase(LAS unsigned char* lds, const Gemm g, const Sched& S, const Epi& E, int tid) {
;     ...
;             PG8_BAR; PG8_WAIT_L(0); PG8_MMA(0, 1, At, B1); PG8_BAR;
;             PG8_LDA(At, 1, 1); PG8_STAGE(PG8_SA(1, 0), a3, voffA);
;             PG8_BAR; PG8_WAIT_L(0); PG8_MMA(1, 0, At, B0); PG8_BAR; PG8_SCHED;
;             PG8_STAGE(PG8_SB(1, 1), b3 + hstep, voffB);
;             PG8_WAIT_V(6); PG8_BAR; PG8_MMA(1, 1, At, B1); PG8_BAR;
	s_waitcnt lgkmcnt(0)
	s_setprio 1
	s_waitcnt lgkmcnt(0)
	v_mfma_f32_16x16x32_bf16 v[108:111], v[212:215], v[168:171], v[108:111]
	v_mfma_f32_16x16x32_bf16 v[104:107], v[220:223], v[168:171], v[104:107]
	v_mfma_f32_16x16x32_bf16 v[92:95], v[212:215], v[188:191], v[92:95]
	v_mfma_f32_16x16x32_bf16 v[88:91], v[220:223], v[188:191], v[88:91]
	v_mfma_f32_16x16x32_bf16 v[76:79], v[212:215], v[196:199], v[76:79]
	v_mfma_f32_16x16x32_bf16 v[72:75], v[220:223], v[196:199], v[72:75]
	v_mfma_f32_16x16x32_bf16 v[68:71], v[212:215], v[204:207], v[68:71]
	v_mfma_f32_16x16x32_bf16 v[64:67], v[220:223], v[204:207], v[64:67]
	v_mfma_f32_16x16x32_bf16 v[108:111], v[216:219], v[184:187], v[108:111]
	v_mfma_f32_16x16x32_bf16 v[104:107], v[224:227], v[184:187], v[104:107]
	v_mfma_f32_16x16x32_bf16 v[92:95], v[216:219], v[192:195], v[92:95]
	v_mfma_f32_16x16x32_bf16 v[88:91], v[224:227], v[192:195], v[88:91]
	v_mfma_f32_16x16x32_bf16 v[76:79], v[216:219], v[200:203], v[76:79]
	v_mfma_f32_16x16x32_bf16 v[72:75], v[224:227], v[200:203], v[72:75]
	v_mfma_f32_16x16x32_bf16 v[68:71], v[216:219], v[208:211], v[68:71]
	v_mfma_f32_16x16x32_bf16 v[64:67], v[224:227], v[208:211], v[64:67]
	s_setprio 0
	s_mov_b32 m0, s92
	v_lshl_add_u64 v[152:153], v[230:231], 0, s[8:9]
	s_barrier
	ds_read_b128 v[168:171], v143 offset:49152
	ds_read_b128 v[184:187], v143 offset:50176
	ds_read_b128 v[188:191], v143 offset:51200
	ds_read_b128 v[192:195], v143 offset:52224
	ds_read_b128 v[196:199], v143 offset:53248
	ds_read_b128 v[200:203], v143 offset:54272
	ds_read_b128 v[204:207], v143 offset:55296
	ds_read_b128 v[208:211], v143 offset:56320
	global_load_lds_dwordx4 v[152:153], off
	v_lshl_add_u64 v[152:153], v[232:233], 0, s[8:9]
	s_mov_b32 m0, s93
	s_nop 0
	global_load_lds_dwordx4 v[152:153], off
	s_barrier
	s_waitcnt lgkmcnt(0)
	s_setprio 1
	s_waitcnt lgkmcnt(0)
	v_mfma_f32_16x16x32_bf16 v[60:63], v[144:147], v[168:171], v[60:63]
	v_mfma_f32_16x16x32_bf16 v[56:59], v[160:163], v[168:171], v[56:59]
	v_mfma_f32_16x16x32_bf16 v[52:55], v[144:147], v[188:191], v[52:55]
	v_mfma_f32_16x16x32_bf16 v[48:51], v[160:163], v[188:191], v[48:51]
	v_mfma_f32_16x16x32_bf16 v[36:39], v[144:147], v[196:199], v[36:39]
	v_mfma_f32_16x16x32_bf16 v[32:35], v[160:163], v[196:199], v[32:35]
	v_mfma_f32_16x16x32_bf16 v[20:23], v[144:147], v[204:207], v[20:23]
	v_mfma_f32_16x16x32_bf16 v[16:19], v[160:163], v[204:207], v[16:19]
	v_mfma_f32_16x16x32_bf16 v[60:63], v[148:151], v[184:187], v[60:63]
	v_mfma_f32_16x16x32_bf16 v[56:59], v[164:167], v[184:187], v[56:59]
	v_mfma_f32_16x16x32_bf16 v[52:55], v[148:151], v[192:195], v[52:55]
	v_mfma_f32_16x16x32_bf16 v[48:51], v[164:167], v[192:195], v[48:51]
	v_mfma_f32_16x16x32_bf16 v[36:39], v[148:151], v[200:203], v[36:39]
	v_mfma_f32_16x16x32_bf16 v[32:35], v[164:167], v[200:203], v[32:35]
	v_mfma_f32_16x16x32_bf16 v[20:23], v[148:151], v[208:211], v[20:23]
	v_mfma_f32_16x16x32_bf16 v[16:19], v[164:167], v[208:211], v[16:19]
	s_setprio 0
	s_barrier
	s_add_i32 s1, s17, s85
	v_lshl_add_u64 v[144:145], v[234:235], 0, s[8:9]
	s_mov_b32 m0, s1
	s_nop 0
	global_load_lds_dwordx4 v[144:145], off
	v_lshl_add_u64 v[144:145], v[236:237], 0, s[8:9]
	s_add_i32 m0, s1, 0x2000
	s_nop 0
	global_load_lds_dwordx4 v[144:145], off
	s_waitcnt vmcnt(6)
	s_barrier
	s_setprio 1
	v_mfma_f32_16x16x32_bf16 v[44:47], v[212:215], v[168:171], v[44:47]
	v_mfma_f32_16x16x32_bf16 v[40:43], v[220:223], v[168:171], v[40:43]
	v_mfma_f32_16x16x32_bf16 v[28:31], v[212:215], v[188:191], v[28:31]
	v_mfma_f32_16x16x32_bf16 v[24:27], v[220:223], v[188:191], v[24:27]
	v_mfma_f32_16x16x32_bf16 v[12:15], v[212:215], v[196:199], v[12:15]
	v_mfma_f32_16x16x32_bf16 v[8:11], v[220:223], v[196:199], v[8:11]
	v_mfma_f32_16x16x32_bf16 v[4:7], v[212:215], v[204:207], v[4:7]
	v_mfma_f32_16x16x32_bf16 v[0:3], v[220:223], v[204:207], v[0:3]
	v_mfma_f32_16x16x32_bf16 v[44:47], v[216:219], v[184:187], v[44:47]
	v_mfma_f32_16x16x32_bf16 v[40:43], v[224:227], v[184:187], v[40:43]
	v_mfma_f32_16x16x32_bf16 v[28:31], v[216:219], v[192:195], v[28:31]
	v_mfma_f32_16x16x32_bf16 v[24:27], v[224:227], v[192:195], v[24:27]
	v_mfma_f32_16x16x32_bf16 v[12:15], v[216:219], v[200:203], v[12:15]
	v_mfma_f32_16x16x32_bf16 v[8:11], v[224:227], v[200:203], v[8:11]
	v_mfma_f32_16x16x32_bf16 v[4:7], v[216:219], v[208:211], v[4:7]
	v_mfma_f32_16x16x32_bf16 v[0:3], v[224:227], v[208:211], v[0:3]
	s_setprio 0
	s_add_u32 vcc_lo, vcc_lo, 0x100
	s_addc_u32 vcc_hi, vcc_hi, 0
	s_add_u32 s96, s96, 0x100
	s_addc_u32 s65, s65, 0
	s_cmp_ge_u32 s0, s94
	s_mov_b32 s34, s0
	s_barrier
	s_cbranch_scc1 .Lpeel_exit_plain

; #define PG8_STAGE(bufoff, gbase, voff) do { _Pragma("unroll") for (int _i = 0; _i < 2; ++_i) \
;         __builtin_amdgcn_global_load_lds((const unsigned*)((const char*)(gbase) + (voff)[_i]), (LAS unsigned*)(lds + (bufoff) + ldsw + _i * 8192), 16, 0, 0); } while (0)
; #define PG8_WAIT_V(n) asm volatile("s_waitcnt vmcnt(" #n ")" ::: "memory")
; #define PG8_BAR __builtin_amdgcn_s_barrier()
; #define tid fresh_tid(wave_s)
; template <class Epi, class Sched>
; __device__ __forceinline__ void gemm_phase(LAS unsigned char* lds, const Gemm g, const Sched& S, const Epi& E, int tid) {
;     ...
;     for (int i = 0; i < 2; ++i) { int R, C; stage_rc(tid * 16 + i * 8192, R, C); const int Rb = Epi::PERM ? ((R & ~31) + perm32(R & 31)) : R;
;         voffA[i] = (unsigned)(R * K + C) * 2u; voffB[i] = (unsigned)(Rb * K + C) * 2u; }
;     const size_t kstep = (size_t)(BK * 2);
;     const size_t hstep = (size_t)HALF * K * 2;
;     const size_t tstep = 2 * hstep;
;     const unsigned ldsw = (unsigned)wid * 1024u;
;     const int aoff = lds_byte(wr * 64 + fr, fq * 8), boff = lds_byte(wc * 32 + fr, fq * 8);
;     ...
;     Unit cur, nxt; int ui = 0;
;     if (!S.next(0, cur)) return;
;     f32x4 acc[2][2][4][2];
; #pragma unroll
;     for (int a = 0; a < 2; ++a)
; #pragma unroll
;         for (int b = 0; b < 2; ++b)
; #pragma unroll
;             for (int m = 0; m < 4; ++m)
; #pragma unroll
;                 for (int n = 0; n < 2; ++n) acc[a][b][m][n] = (f32x4){0.f, 0.f, 0.f, 0.f};
;     bf16x8 At[4][2], B0[2][2], B1[2][2];
;     const char* cA = (const char*)g.A + (size_t)cur.pm * tstep; const char* cB = (const char*)g.Bt + (size_t)cur.pn * tstep;
;     PG8_STAGE(PG8_SB(0, 0), cB, voffB); PG8_STAGE(PG8_SA(0, 0), cA, voffA); PG8_STAGE(PG8_SB(0, 1), cB + hstep, voffB); PG8_STAGE(PG8_SA(0, 1), cA + hstep, voffA);
;     if (wr == 1) PG8_BAR;
;     PG8_WAIT_V(4); PG8_BAR;
;     PG8_STAGE(PG8_SB(1, 0), cB + kstep, voffB); PG8_STAGE(PG8_SA(1, 0), cA + kstep, voffA); PG8_STAGE(PG8_SB(1, 1), cB + hstep + kstep, voffB);
;     PG8_WAIT_V(6); PG8_BAR;
.LBB0_111:
	s_add_u32 s22, s26, 0x4000000
	v_lshrrev_b32_e32 v16, 1, v14
	s_addc_u32 s23, s27, 0
	v_and_b32_e32 v16, 24, v16
	s_lshl_b32 s0, s0, 5
	v_and_b32_e32 v15, 15, v14
	v_lshlrev_b32_e32 v17, 1, v16
	v_lshlrev_b32_e32 v14, 2, v14
	s_and_b32 s14, s0, 0x60
	s_add_i32 m0, s39, 0x18000
	v_lshl_add_u64 v[6:7], v[6:7], 0, s[8:9]
	s_sext_i32_i16 s52, s6
	v_lshl_or_b32 v142, s1, 6, v15
	v_lshl_or_b32 v15, v15, 6, v17
	s_lshl_b32 s1, s1, 13
	v_and_b32_e32 v14, 32, v14
	s_lshl_b32 s0, s14, 7
	s_waitcnt vmcnt(4)
	s_barrier
	global_load_lds_dwordx4 v[6:7], off
	v_lshl_add_u64 v[4:5], v[4:5], 0, s[8:9]
	s_add_i32 m0, s39, 0x1a000
	s_add_i32 s6, s39, 0x8000
	s_add_i32 s50, s39, 0xa000
	v_bitop3_b32 v143, s0, v15, v14 bitop3:0xf6
	global_load_lds_dwordx4 v[4:5], off
	v_lshl_add_u64 v[2:3], v[2:3], 0, s[8:9]
	s_mov_b32 m0, s6
	s_add_u32 s0, s42, 0x40080
	v_bitop3_b32 v17, v15, s1, v14 bitop3:0xde
	global_load_lds_dwordx4 v[2:3], off
	v_lshl_add_u64 v[0:1], v[0:1], 0, s[8:9]
	s_mov_b32 m0, s50
	s_addc_u32 s1, s43, 0
	global_load_lds_dwordx4 v[0:1], off
	s_add_i32 m0, s39, 0x1c000
	v_lshl_add_u64 v[0:1], s[0:1], 0, v[154:155]
	global_load_lds_dwordx4 v[0:1], off
	v_lshl_add_u64 v[0:1], s[0:1], 0, v[128:129]
	s_add_i32 m0, s39, 0x1e000
	v_or_b32_e32 v144, s14, v16
	global_load_lds_dwordx4 v[0:1], off
	v_lshlrev_b32_e32 v0, 14, v12
	v_and_b32_e32 v0, 0xffff8000, v0
	v_lshl_add_u32 v0, v11, 11, v0
	v_and_b32_e32 v1, 1, v12
	v_lshl_or_b32 v0, v1, 6, v0
	v_lshl_add_u32 v134, v13, 1, v0
	v_lshlrev_b32_e32 v0, 14, v8
	v_and_b32_e32 v0, 0xffff8000, v0
	s_waitcnt vmcnt(0)
	v_lshl_add_u32 v0, v9, 11, v0
	v_and_b32_e32 v1, 1, v8
	v_lshl_or_b32 v0, v1, 6, v0
	v_mov_b32_e32 v135, v155
	v_lshl_add_u32 v136, v10, 1, v0
	v_mov_b32_e32 v137, v155
	s_mov_b32 s51, 0
	v_add_u32_e32 v145, 0, v17
	s_barrier

; #define PG8_STAGE(bufoff, gbase, voff) do { _Pragma("unroll") for (int _i = 0; _i < 2; ++_i) \
;         __builtin_amdgcn_global_load_lds((const unsigned*)((const char*)(gbase) + (voff)[_i]), (LAS unsigned*)(lds + (bufoff) + ldsw + _i * 8192), 16, 0, 0); } while (0)
; #define PG8_LDA(dst, b, h) do { _Pragma("unroll") for (int m = 0; m < 4; ++m) _Pragma("unroll") for (int k = 0; k < 2; ++k) dst[m][k] = *(const LAS bf16x8*)(lds + PG8_SA(b, h) + aoff + m * 2048 + k * 1024); } while (0)
; #define PG8_LDB(dst, b, h) do { _Pragma("unroll") for (int n = 0; n < 2; ++n) _Pragma("unroll") for (int k = 0; k < 2; ++k) dst[n][k] = *(const LAS bf16x8*)(lds + PG8_SB(b, h) + boff + n * 2048 + k * 1024); } while (0)
; #define PG8_MMA(ai, bj, At, Bt) do { __builtin_amdgcn_s_setprio(1); _Pragma("unroll") for (int m = 0; m < 4; ++m) _Pragma("unroll") for (int n = 0; n < 2; ++n) _Pragma("unroll") for (int k = 0; k < 2; ++k) \
;         acc[ai][bj][m][n] = __builtin_amdgcn_mfma_f32_16x16x32_bf16(Bt[n][k], At[m][k], acc[ai][bj][m][n], 0, 0, 0); __builtin_amdgcn_s_setprio(0); } while (0)
; #define PG8_WAIT_L(n) asm volatile("s_waitcnt lgkmcnt(" #n ")" ::: "memory")
; template <class Epi, class Sched>
; __device__ __forceinline__ void gemm_phase(LAS unsigned char* lds, const Gemm g, const Sched& S, const Epi& E, int tid) {
;     ...
;         const bool has_next = S.next(ui + 1, nxt);
;         const char* nA = has_next ? (const char*)g.A + (size_t)nxt.pm * tstep : cA; const char* nB = has_next ? (const char*)g.Bt + (size_t)nxt.pn * tstep : cB;
;         for (int t = 0; t < nt; t += 2) {
;             const bool last = (t == nt - 2);
;             const char* a1 = cA + (size_t)(t + 1) * kstep;
;             const char* a2 = last ? nA : cA + (size_t)(t + 2) * kstep; const char* b2 = last ? nB : cB + (size_t)(t + 2) * kstep;
;             const char* a3 = a2 + kstep; const char* b3 = b2 + kstep;
;             PG8_LDB(B0, 0, 0); PG8_SCHED; PG8_LDA(At, 0, 0); PG8_STAGE(PG8_SA(1, 1), a1 + hstep, voffA);
;             PG8_WAIT_L(8); PG8_BAR; PG8_WAIT_L(0); PG8_MMA(0, 0, At, B0); PG8_BAR; PG8_SCHED;
;             PG8_LDB(B1, 0, 1); PG8_STAGE(PG8_SB(0, 0), b2, voffB);
;             PG8_BAR; PG8_WAIT_L(0); PG8_MMA(0, 1, At, B1); PG8_BAR;
;             PG8_LDA(At, 0, 1); PG8_STAGE(PG8_SA(0, 0), a2, voffA);
;             PG8_BAR; PG8_WAIT_L(0); PG8_MMA(1, 0, At, B0); PG8_BAR; PG8_SCHED;
.LBB0_114:
	s_ashr_i32 s25, s24, 31
	s_lshl_b64 s[0:1], s[24:25], 19
	v_cmp_lt_i64_e32 vcc, s[28:29], v[158:159]
	s_add_u32 s28, s26, s0
	s_addc_u32 s29, s27, s1
	s_and_b64 s[0:1], vcc, exec
	s_cselect_b32 s25, s29, s41
	s_cselect_b32 s53, s28, s40
	s_ashr_i32 s15, s14, 31
	s_lshl_b64 s[0:1], s[14:15], 19
	s_add_u32 s30, s19, s0
	s_addc_u32 s31, s44, s1
	s_and_b64 s[0:1], vcc, exec
	s_cselect_b32 s15, s31, s43
	s_cselect_b32 s55, s30, s42
	s_add_u32 s40, s40, 0x40080
	s_addc_u32 s41, s41, 0
	s_add_u32 s58, s42, 0x100
	s_addc_u32 s60, s43, 0
	s_mov_b32 s61, -2
	s_add_u32 s0, s40, 0xfffc0080
	s_addc_u32 s1, s41, -1
	s_add_i32 s17, 0, 0x10000
	v_add_u32_e32 v160, s17, v143
	ds_read_b128 v[138:141], v160
	ds_read_b128 v[146:149], v160 offset:1024
	ds_read_b128 v[150:153], v160 offset:2048
	ds_read_b128 v[160:163], v160 offset:3072
	s_cmp_eq_u32 s61, 12
	s_cselect_b32 s43, s25, s1
	s_cselect_b32 s42, s53, s0
	s_cselect_b32 s35, s15, s60
	s_cselect_b32 s34, s55, s58
	v_lshl_add_u64 v[208:209], s[40:41], 0, v[134:135]
	s_add_i32 m0, s39, 0xc000
	ds_read_b128 v[164:167], v145
	ds_read_b128 v[168:171], v145 offset:1024
	ds_read_b128 v[184:187], v145 offset:2048
	ds_read_b128 v[188:191], v145 offset:3072
	ds_read_b128 v[192:195], v145 offset:4096
	ds_read_b128 v[196:199], v145 offset:5120
	ds_read_b128 v[200:203], v145 offset:6144
	ds_read_b128 v[204:207], v145 offset:7168
	global_load_lds_dwordx4 v[208:209], off
	v_lshl_add_u64 v[208:209], s[40:41], 0, v[136:137]
	s_add_i32 m0, s39, 0xe000
	s_nop 0
	global_load_lds_dwordx4 v[208:209], off
	s_waitcnt lgkmcnt(8)
	s_barrier
	s_waitcnt lgkmcnt(0)
	s_setprio 1
	s_waitcnt lgkmcnt(0)
	v_mfma_f32_16x16x32_bf16 v[124:127], v[138:141], v[164:167], 0
	v_mfma_f32_16x16x32_bf16 v[120:123], v[150:153], v[164:167], 0
	v_mfma_f32_16x16x32_bf16 v[108:111], v[138:141], v[184:187], 0
	v_mfma_f32_16x16x32_bf16 v[104:107], v[150:153], v[184:187], 0
	v_mfma_f32_16x16x32_bf16 v[92:95], v[138:141], v[192:195], 0
	v_mfma_f32_16x16x32_bf16 v[88:91], v[150:153], v[192:195], 0
	v_mfma_f32_16x16x32_bf16 v[76:79], v[138:141], v[200:203], 0
	v_mfma_f32_16x16x32_bf16 v[72:75], v[150:153], v[200:203], 0
	v_mfma_f32_16x16x32_bf16 v[124:127], v[146:149], v[168:171], v[124:127]
	v_mfma_f32_16x16x32_bf16 v[120:123], v[160:163], v[168:171], v[120:123]
	v_mfma_f32_16x16x32_bf16 v[108:111], v[146:149], v[188:191], v[108:111]
	v_mfma_f32_16x16x32_bf16 v[104:107], v[160:163], v[188:191], v[104:107]
	v_mfma_f32_16x16x32_bf16 v[92:95], v[146:149], v[196:199], v[92:95]
	v_mfma_f32_16x16x32_bf16 v[88:91], v[160:163], v[196:199], v[88:91]
	v_mfma_f32_16x16x32_bf16 v[76:79], v[146:149], v[204:207], v[76:79]
	v_mfma_f32_16x16x32_bf16 v[72:75], v[160:163], v[204:207], v[72:75]
	s_setprio 0
	s_barrier
	s_add_i32 s63, 0, 0x14000
	s_add_i32 s0, s17, s45
	v_add_u32_e32 v183, s63, v143
	v_lshl_add_u64 v[224:225], s[34:35], 0, v[154:155]
	s_mov_b32 m0, s0
	ds_read_b128 v[208:211], v183
	ds_read_b128 v[212:215], v183 offset:1024
	ds_read_b128 v[216:219], v183 offset:2048
	ds_read_b128 v[220:223], v183 offset:3072
	global_load_lds_dwordx4 v[224:225], off
	v_lshl_add_u64 v[226:227], s[34:35], 0, v[128:129]
	s_add_i32 m0, s0, 0x2000
	s_nop 0
	global_load_lds_dwordx4 v[226:227], off
	s_barrier
	s_waitcnt lgkmcnt(0)
	s_setprio 1
	s_waitcnt lgkmcnt(0)
	v_mfma_f32_16x16x32_bf16 v[116:119], v[208:211], v[164:167], 0
	v_mfma_f32_16x16x32_bf16 v[112:115], v[216:219], v[164:167], 0
	v_mfma_f32_16x16x32_bf16 v[100:103], v[208:211], v[184:187], 0
	v_mfma_f32_16x16x32_bf16 v[96:99], v[216:219], v[184:187], 0
	v_mfma_f32_16x16x32_bf16 v[84:87], v[208:211], v[192:195], 0
	v_mfma_f32_16x16x32_bf16 v[80:83], v[216:219], v[192:195], 0
	v_mfma_f32_16x16x32_bf16 v[68:71], v[208:211], v[200:203], 0
	v_mfma_f32_16x16x32_bf16 v[64:67], v[216:219], v[200:203], 0
	v_mfma_f32_16x16x32_bf16 v[116:119], v[212:215], v[168:171], v[116:119]
	v_mfma_f32_16x16x32_bf16 v[112:115], v[220:223], v[168:171], v[112:115]
	v_mfma_f32_16x16x32_bf16 v[100:103], v[212:215], v[188:191], v[100:103]
	v_mfma_f32_16x16x32_bf16 v[96:99], v[220:223], v[188:191], v[96:99]
	v_mfma_f32_16x16x32_bf16 v[84:87], v[212:215], v[196:199], v[84:87]
	v_mfma_f32_16x16x32_bf16 v[80:83], v[220:223], v[196:199], v[80:83]
	v_mfma_f32_16x16x32_bf16 v[68:71], v[212:215], v[204:207], v[68:71]
	v_mfma_f32_16x16x32_bf16 v[64:67], v[220:223], v[204:207], v[64:67]
	s_setprio 0
	s_mov_b32 m0, s39
	v_lshl_add_u64 v[228:229], s[42:43], 0, v[132:133]
	s_barrier
	ds_read_b128 v[164:167], v145 offset:16384
	ds_read_b128 v[168:171], v145 offset:17408
	ds_read_b128 v[184:187], v145 offset:18432
	ds_read_b128 v[188:191], v145 offset:19456
	ds_read_b128 v[192:195], v145 offset:20480
	ds_read_b128 v[196:199], v145 offset:21504
	ds_read_b128 v[200:203], v145 offset:22528
	ds_read_b128 v[204:207], v145 offset:23552
	global_load_lds_dwordx4 v[228:229], off
	v_lshl_add_u64 v[230:231], s[42:43], 0, v[130:131]
	s_mov_b32 m0, s47
	s_nop 0
	global_load_lds_dwordx4 v[230:231], off
	s_barrier
	s_waitcnt lgkmcnt(0)
	s_setprio 1
	s_waitcnt lgkmcnt(0)
	v_mfma_f32_16x16x32_bf16 v[60:63], v[138:141], v[164:167], 0
	v_mfma_f32_16x16x32_bf16 v[56:59], v[150:153], v[164:167], 0
	v_mfma_f32_16x16x32_bf16 v[44:47], v[138:141], v[184:187], 0
	v_mfma_f32_16x16x32_bf16 v[40:43], v[150:153], v[184:187], 0
	v_mfma_f32_16x16x32_bf16 v[28:31], v[138:141], v[192:195], 0
	v_mfma_f32_16x16x32_bf16 v[24:27], v[150:153], v[192:195], 0
	v_mfma_f32_16x16x32_bf16 v[12:15], v[138:141], v[200:203], 0
	v_mfma_f32_16x16x32_bf16 v[8:11], v[150:153], v[200:203], 0
	v_mfma_f32_16x16x32_bf16 v[60:63], v[146:149], v[168:171], v[60:63]
	v_mfma_f32_16x16x32_bf16 v[56:59], v[160:163], v[168:171], v[56:59]
	v_mfma_f32_16x16x32_bf16 v[44:47], v[146:149], v[188:191], v[44:47]
	v_mfma_f32_16x16x32_bf16 v[40:43], v[160:163], v[188:191], v[40:43]
	v_mfma_f32_16x16x32_bf16 v[28:31], v[146:149], v[196:199], v[28:31]
	v_mfma_f32_16x16x32_bf16 v[24:27], v[160:163], v[196:199], v[24:27]
	v_mfma_f32_16x16x32_bf16 v[12:15], v[146:149], v[204:207], v[12:15]
	v_mfma_f32_16x16x32_bf16 v[8:11], v[160:163], v[204:207], v[8:11]
	s_setprio 0
	s_barrier
; #define PG8_STAGE(bufoff, gbase, voff) do { _Pragma("unroll") for (int _i = 0; _i < 2; ++_i) \
;         __builtin_amdgcn_global_load_lds((const unsigned*)((const char*)(gbase) + (voff)[_i]), (LAS unsigned*)(lds + (bufoff) + ldsw + _i * 8192), 16, 0, 0); } while (0)
; #define PG8_LDA(dst, b, h) do { _Pragma("unroll") for (int m = 0; m < 4; ++m) _Pragma("unroll") for (int k = 0; k < 2; ++k) dst[m][k] = *(const LAS bf16x8*)(lds + PG8_SA(b, h) + aoff + m * 2048 + k * 1024); } while (0)
; #define PG8_LDB(dst, b, h) do { _Pragma("unroll") for (int n = 0; n < 2; ++n) _Pragma("unroll") for (int k = 0; k < 2; ++k) dst[n][k] = *(const LAS bf16x8*)(lds + PG8_SB(b, h) + boff + n * 2048 + k * 1024); } while (0)
; #define PG8_MMA(ai, bj, At, Bt) do { __builtin_amdgcn_s_setprio(1); _Pragma("unroll") for (int m = 0; m < 4; ++m) _Pragma("unroll") for (int n = 0; n < 2; ++n) _Pragma("unroll") for (int k = 0; k < 2; ++k) \
;         acc[ai][bj][m][n] = __builtin_amdgcn_mfma_f32_16x16x32_bf16(Bt[n][k], At[m][k], acc[ai][bj][m][n], 0, 0, 0); __builtin_amdgcn_s_setprio(0); } while (0)
; #define PG8_WAIT_V(n) asm volatile("s_waitcnt vmcnt(" #n ")" ::: "memory")
; #define PG8_WAIT_L(n) asm volatile("s_waitcnt lgkmcnt(" #n ")" ::: "memory")
; #define PG8_BAR __builtin_amdgcn_s_barrier()
; #define PG8_SCHED __builtin_amdgcn_sched_barrier(0)
; template <class Epi, class Sched>
; __device__ __forceinline__ void gemm_phase(LAS unsigned char* lds, const Gemm g, const Sched& S, const Epi& E, int tid) {
;     ...
;             PG8_STAGE(PG8_SB(0, 1), b2 + hstep, voffB);
;             PG8_WAIT_V(6); PG8_BAR; PG8_MMA(1, 1, At, B1); PG8_BAR;
;             PG8_LDB(B0, 1, 0); PG8_SCHED; PG8_LDA(At, 1, 0); PG8_STAGE(PG8_SA(0, 1), a2 + hstep, voffA);
;             PG8_WAIT_L(8); PG8_BAR; PG8_WAIT_L(0); PG8_MMA(0, 0, At, B0); PG8_BAR; PG8_SCHED;
;             PG8_LDB(B1, 1, 1); PG8_STAGE(PG8_SB(1, 0), b3, voffB);
;             PG8_BAR; PG8_WAIT_L(0); PG8_MMA(0, 1, At, B1); PG8_BAR;
	s_add_u32 s0, s34, 0x40000
	s_addc_u32 s1, s35, 0
	s_add_i32 s17, s63, s45
	v_lshl_add_u64 v[138:139], s[0:1], 0, v[154:155]
	s_mov_b32 m0, s17
	s_nop 0
	global_load_lds_dwordx4 v[138:139], off
	v_lshl_add_u64 v[138:139], s[0:1], 0, v[128:129]
	s_add_i32 m0, s17, 0x2000
	s_nop 0
	global_load_lds_dwordx4 v[138:139], off
	s_waitcnt vmcnt(16)
	s_barrier
	s_setprio 1
	v_mfma_f32_16x16x32_bf16 v[52:55], v[208:211], v[164:167], 0
	v_mfma_f32_16x16x32_bf16 v[48:51], v[216:219], v[164:167], 0
	v_mfma_f32_16x16x32_bf16 v[36:39], v[208:211], v[184:187], 0
	v_mfma_f32_16x16x32_bf16 v[32:35], v[216:219], v[184:187], 0
	v_mfma_f32_16x16x32_bf16 v[20:23], v[208:211], v[192:195], 0
	v_mfma_f32_16x16x32_bf16 v[16:19], v[216:219], v[192:195], 0
	v_mfma_f32_16x16x32_bf16 v[4:7], v[208:211], v[200:203], 0
	v_mfma_f32_16x16x32_bf16 v[0:3], v[216:219], v[200:203], 0
	v_mfma_f32_16x16x32_bf16 v[52:55], v[212:215], v[168:171], v[52:55]
	v_mfma_f32_16x16x32_bf16 v[48:51], v[220:223], v[168:171], v[48:51]
	v_mfma_f32_16x16x32_bf16 v[36:39], v[212:215], v[188:191], v[36:39]
	v_mfma_f32_16x16x32_bf16 v[32:35], v[220:223], v[188:191], v[32:35]
	v_mfma_f32_16x16x32_bf16 v[20:23], v[212:215], v[196:199], v[20:23]
	v_mfma_f32_16x16x32_bf16 v[16:19], v[220:223], v[196:199], v[16:19]
	v_mfma_f32_16x16x32_bf16 v[4:7], v[212:215], v[204:207], v[4:7]
	v_mfma_f32_16x16x32_bf16 v[0:3], v[220:223], v[204:207], v[0:3]
	s_setprio 0
	s_add_i32 s17, 0, 0x18000
	v_add_u32_e32 v160, s17, v143
	s_barrier
	ds_read_b128 v[138:141], v160
	ds_read_b128 v[146:149], v160 offset:1024
	ds_read_b128 v[150:153], v160 offset:2048
	ds_read_b128 v[160:163], v160 offset:3072
	s_add_u32 s0, s42, 0x40000
	s_addc_u32 s1, s43, 0
	s_mov_b32 m0, s48
	v_lshl_add_u64 v[208:209], s[0:1], 0, v[132:133]
	ds_read_b128 v[164:167], v145 offset:32768
	ds_read_b128 v[168:171], v145 offset:33792
	ds_read_b128 v[184:187], v145 offset:34816
	ds_read_b128 v[188:191], v145 offset:35840
	ds_read_b128 v[192:195], v145 offset:36864
	ds_read_b128 v[196:199], v145 offset:37888
	ds_read_b128 v[200:203], v145 offset:38912
	ds_read_b128 v[204:207], v145 offset:39936
	global_load_lds_dwordx4 v[208:209], off
	v_lshl_add_u64 v[208:209], s[0:1], 0, v[130:131]
	s_mov_b32 m0, s49
	s_nop 0
	global_load_lds_dwordx4 v[208:209], off
	s_waitcnt lgkmcnt(8)
	s_barrier
	s_waitcnt lgkmcnt(0)
	s_setprio 1
	s_waitcnt lgkmcnt(0)
	v_mfma_f32_16x16x32_bf16 v[124:127], v[138:141], v[164:167], v[124:127]
	v_mfma_f32_16x16x32_bf16 v[120:123], v[150:153], v[164:167], v[120:123]
	v_mfma_f32_16x16x32_bf16 v[108:111], v[138:141], v[184:187], v[108:111]
	v_mfma_f32_16x16x32_bf16 v[104:107], v[150:153], v[184:187], v[104:107]
	v_mfma_f32_16x16x32_bf16 v[92:95], v[138:141], v[192:195], v[92:95]
	v_mfma_f32_16x16x32_bf16 v[88:91], v[150:153], v[192:195], v[88:91]
	v_mfma_f32_16x16x32_bf16 v[76:79], v[138:141], v[200:203], v[76:79]
	v_mfma_f32_16x16x32_bf16 v[72:75], v[150:153], v[200:203], v[72:75]
	v_mfma_f32_16x16x32_bf16 v[124:127], v[146:149], v[168:171], v[124:127]
	v_mfma_f32_16x16x32_bf16 v[120:123], v[160:163], v[168:171], v[120:123]
	v_mfma_f32_16x16x32_bf16 v[108:111], v[146:149], v[188:191], v[108:111]
	v_mfma_f32_16x16x32_bf16 v[104:107], v[160:163], v[188:191], v[104:107]
	v_mfma_f32_16x16x32_bf16 v[92:95], v[146:149], v[196:199], v[92:95]
	v_mfma_f32_16x16x32_bf16 v[88:91], v[160:163], v[196:199], v[88:91]
	v_mfma_f32_16x16x32_bf16 v[76:79], v[146:149], v[204:207], v[76:79]
	v_mfma_f32_16x16x32_bf16 v[72:75], v[160:163], v[204:207], v[72:75]
	s_setprio 0
	s_barrier
	s_add_i32 s42, 0, 0x1c000
	s_add_i32 s0, s17, s45
	v_add_u32_e32 v183, s42, v143
	v_lshl_add_u64 v[224:225], v[224:225], 0, s[8:9]
	s_mov_b32 m0, s0
	ds_read_b128 v[208:211], v183
	ds_read_b128 v[212:215], v183 offset:1024
	ds_read_b128 v[216:219], v183 offset:2048
	ds_read_b128 v[220:223], v183 offset:3072
	global_load_lds_dwordx4 v[224:225], off
	v_lshl_add_u64 v[224:225], v[226:227], 0, s[8:9]
	s_add_i32 m0, s0, 0x2000
	s_nop 0
	global_load_lds_dwordx4 v[224:225], off
	s_waitcnt vmcnt(10)
	s_barrier
; #define PG8_STAGE(bufoff, gbase, voff) do { _Pragma("unroll") for (int _i = 0; _i < 2; ++_i) \
;         __builtin_amdgcn_global_load_lds((const unsigned*)((const char*)(gbase) + (voff)[_i]), (LAS unsigned*)(lds + (bufoff) + ldsw + _i * 8192), 16, 0, 0); } while (0)
; #define PG8_LDA(dst, b, h) do { _Pragma("unroll") for (int m = 0; m < 4; ++m) _Pragma("unroll") for (int k = 0; k < 2; ++k) dst[m][k] = *(const LAS bf16x8*)(lds + PG8_SA(b, h) + aoff + m * 2048 + k * 1024); } while (0)
; #define PG8_MMA(ai, bj, At, Bt) do { __builtin_amdgcn_s_setprio(1); _Pragma("unroll") for (int m = 0; m < 4; ++m) _Pragma("unroll") for (int n = 0; n < 2; ++n) _Pragma("unroll") for (int k = 0; k < 2; ++k) \
;         acc[ai][bj][m][n] = __builtin_amdgcn_mfma_f32_16x16x32_bf16(Bt[n][k], At[m][k], acc[ai][bj][m][n], 0, 0, 0); __builtin_amdgcn_s_setprio(0); } while (0)
; #define PG8_WAIT_V(n) asm volatile("s_waitcnt vmcnt(" #n ")" ::: "memory")
; #define PG8_WAIT_L(n) asm volatile("s_waitcnt lgkmcnt(" #n ")" ::: "memory")
; #define PG8_BAR __builtin_amdgcn_s_barrier()
; #define PG8_SCHED __builtin_amdgcn_sched_barrier(0)
; template <class Epi, class Sched>
; __device__ __forceinline__ void gemm_phase(LAS unsigned char* lds, const Gemm g, const Sched& S, const Epi& E, int tid) {
;     ...
;             PG8_BAR; PG8_WAIT_L(0); PG8_MMA(0, 1, At, B1); PG8_BAR;
;             PG8_LDA(At, 1, 1); PG8_STAGE(PG8_SA(1, 0), a3, voffA);
;             PG8_BAR; PG8_WAIT_L(0); PG8_MMA(1, 0, At, B0); PG8_BAR; PG8_SCHED;
;             PG8_STAGE(PG8_SB(1, 1), b3 + hstep, voffB);
;             PG8_WAIT_V(6); PG8_BAR; PG8_MMA(1, 1, At, B1); PG8_BAR;
	s_waitcnt lgkmcnt(0)
	s_setprio 1
	s_waitcnt lgkmcnt(0)
	v_mfma_f32_16x16x32_bf16 v[116:119], v[208:211], v[164:167], v[116:119]
	v_mfma_f32_16x16x32_bf16 v[112:115], v[216:219], v[164:167], v[112:115]
	v_mfma_f32_16x16x32_bf16 v[100:103], v[208:211], v[184:187], v[100:103]
	v_mfma_f32_16x16x32_bf16 v[96:99], v[216:219], v[184:187], v[96:99]
	v_mfma_f32_16x16x32_bf16 v[84:87], v[208:211], v[192:195], v[84:87]
	v_mfma_f32_16x16x32_bf16 v[80:83], v[216:219], v[192:195], v[80:83]
	v_mfma_f32_16x16x32_bf16 v[68:71], v[208:211], v[200:203], v[68:71]
	v_mfma_f32_16x16x32_bf16 v[64:67], v[216:219], v[200:203], v[64:67]
	v_mfma_f32_16x16x32_bf16 v[116:119], v[212:215], v[168:171], v[116:119]
	v_mfma_f32_16x16x32_bf16 v[112:115], v[220:223], v[168:171], v[112:115]
	v_mfma_f32_16x16x32_bf16 v[100:103], v[212:215], v[188:191], v[100:103]
	v_mfma_f32_16x16x32_bf16 v[96:99], v[220:223], v[188:191], v[96:99]
	v_mfma_f32_16x16x32_bf16 v[84:87], v[212:215], v[196:199], v[84:87]
	v_mfma_f32_16x16x32_bf16 v[80:83], v[220:223], v[196:199], v[80:83]
	v_mfma_f32_16x16x32_bf16 v[68:71], v[212:215], v[204:207], v[68:71]
	v_mfma_f32_16x16x32_bf16 v[64:67], v[220:223], v[204:207], v[64:67]
	s_setprio 0
	s_mov_b32 m0, s6
	v_lshl_add_u64 v[224:225], v[228:229], 0, s[8:9]
	s_barrier
	ds_read_b128 v[164:167], v145 offset:49152
	ds_read_b128 v[168:171], v145 offset:50176
	ds_read_b128 v[184:187], v145 offset:51200
	ds_read_b128 v[188:191], v145 offset:52224
	ds_read_b128 v[192:195], v145 offset:53248
	ds_read_b128 v[196:199], v145 offset:54272
	ds_read_b128 v[200:203], v145 offset:55296
	ds_read_b128 v[204:207], v145 offset:56320
	global_load_lds_dwordx4 v[224:225], off
	v_lshl_add_u64 v[224:225], v[230:231], 0, s[8:9]
	s_mov_b32 m0, s50
	s_nop 0
	global_load_lds_dwordx4 v[224:225], off
	s_barrier
	s_waitcnt lgkmcnt(0)
	s_setprio 1
	s_waitcnt lgkmcnt(0)
	v_mfma_f32_16x16x32_bf16 v[60:63], v[138:141], v[164:167], v[60:63]
	v_mfma_f32_16x16x32_bf16 v[56:59], v[150:153], v[164:167], v[56:59]
	v_mfma_f32_16x16x32_bf16 v[44:47], v[138:141], v[184:187], v[44:47]
	v_mfma_f32_16x16x32_bf16 v[40:43], v[150:153], v[184:187], v[40:43]
	v_mfma_f32_16x16x32_bf16 v[28:31], v[138:141], v[192:195], v[28:31]
	v_mfma_f32_16x16x32_bf16 v[24:27], v[150:153], v[192:195], v[24:27]
	v_mfma_f32_16x16x32_bf16 v[12:15], v[138:141], v[200:203], v[12:15]
	v_mfma_f32_16x16x32_bf16 v[8:11], v[150:153], v[200:203], v[8:11]
	v_mfma_f32_16x16x32_bf16 v[60:63], v[146:149], v[168:171], v[60:63]
	v_mfma_f32_16x16x32_bf16 v[56:59], v[160:163], v[168:171], v[56:59]
	v_mfma_f32_16x16x32_bf16 v[44:47], v[146:149], v[188:191], v[44:47]
	v_mfma_f32_16x16x32_bf16 v[40:43], v[160:163], v[188:191], v[40:43]
	v_mfma_f32_16x16x32_bf16 v[28:31], v[146:149], v[196:199], v[28:31]
	v_mfma_f32_16x16x32_bf16 v[24:27], v[160:163], v[196:199], v[24:27]
	v_mfma_f32_16x16x32_bf16 v[12:15], v[146:149], v[204:207], v[12:15]
	v_mfma_f32_16x16x32_bf16 v[8:11], v[160:163], v[204:207], v[8:11]
	s_setprio 0
	s_barrier
	s_add_u32 s0, s34, 0x40080
	s_addc_u32 s1, s35, 0
	s_add_i32 s17, s42, s45
	v_lshl_add_u64 v[138:139], s[0:1], 0, v[154:155]
	s_mov_b32 m0, s17
	s_nop 0
	global_load_lds_dwordx4 v[138:139], off
	v_lshl_add_u64 v[138:139], s[0:1], 0, v[128:129]
	s_add_i32 m0, s17, 0x2000
	s_nop 0
	global_load_lds_dwordx4 v[138:139], off
	s_waitcnt vmcnt(6)
	s_barrier
	s_setprio 1
	v_mfma_f32_16x16x32_bf16 v[52:55], v[208:211], v[164:167], v[52:55]
	v_mfma_f32_16x16x32_bf16 v[48:51], v[216:219], v[164:167], v[48:51]
	v_mfma_f32_16x16x32_bf16 v[36:39], v[208:211], v[184:187], v[36:39]
	v_mfma_f32_16x16x32_bf16 v[32:35], v[216:219], v[184:187], v[32:35]
	v_mfma_f32_16x16x32_bf16 v[20:23], v[208:211], v[192:195], v[20:23]
	v_mfma_f32_16x16x32_bf16 v[16:19], v[216:219], v[192:195], v[16:19]
	v_mfma_f32_16x16x32_bf16 v[4:7], v[208:211], v[200:203], v[4:7]
	v_mfma_f32_16x16x32_bf16 v[0:3], v[216:219], v[200:203], v[0:3]
	v_mfma_f32_16x16x32_bf16 v[52:55], v[212:215], v[168:171], v[52:55]
	v_mfma_f32_16x16x32_bf16 v[48:51], v[220:223], v[168:171], v[48:51]
	v_mfma_f32_16x16x32_bf16 v[36:39], v[212:215], v[188:191], v[36:39]
	v_mfma_f32_16x16x32_bf16 v[32:35], v[220:223], v[188:191], v[32:35]
	v_mfma_f32_16x16x32_bf16 v[20:23], v[212:215], v[196:199], v[20:23]
	v_mfma_f32_16x16x32_bf16 v[16:19], v[220:223], v[196:199], v[16:19]
	v_mfma_f32_16x16x32_bf16 v[4:7], v[212:215], v[204:207], v[4:7]
	v_mfma_f32_16x16x32_bf16 v[0:3], v[220:223], v[204:207], v[0:3]
	s_setprio 0
	s_add_i32 s61, s61, 2
	s_add_u32 s40, s40, 0x100
	s_addc_u32 s41, s41, 0
	s_add_u32 s58, s58, 0x100
	s_addc_u32 s60, s60, 0
	s_cmp_gt_u32 s61, 13
	s_barrier
	s_cbranch_scc1 .Lpeel_exit_swiglu
